# P2 unit order: log-decay column tiles spread one per workgroup (was 2 on the 10-unit workgroups); stacks on v7
# baseline (speedup 1.0000x reference)
;     __device__ __forceinline__ bool next(int i, Unit& u) const { if (!base.next(i >> 1, u)) return false; if (i & 1) { u.pm += 64; u.pn += 8; } return true; }
;     __device__ __forceinline__ bool next(int i, Unit& u) const { if (!base.next(i, u)) return false; const int p = u.pn;
;         u.pn = p < 16 ? 22 + p : p < 20 ? p - 16 : p < 24 ? p - 20 + 12 : p < 28 ? p - 24 + 4 : p < 32 ? p - 28 + 8 : p - 32 + 16; return true; }
; template <class Epi, class Sched, bool ALIGN_EPI = false, bool SP2 = false>
; __device__ __forceinline__ void gemm_phase(PG8_LAS unsigned char* lds, const Gemm g, const Sched& S, const Epi& E) {
;     ...
;         for (int a = 0; a < 2; ++a)
; #pragma unroll
;             for (int b = 0; b < 2; ++b)
; #pragma unroll
;                 for (int m = 0; m < 4; ++m)
; #pragma unroll
;                     for (int n = 0; n < 2; ++n) acc[a][b][m][n] = (f32x4){0.f, 0.f, 0.f, 0.f};
;         cur = nxt; cA = nA; cB = nB; ++ui;
.LBB0_203:
	s_mul_i32 s3, s21, s3
	s_sub_i32 s3, s20, s3
	s_add_i32 s20, s1, s3
	s_add_i32 s22, s22, s21
	s_sub_u32 s3, s21, 24
	s_cmp_lt_u32 s3, 8
	s_cbranch_scc0 .Lp2_nodelta
	s_bfe_u32 s3, s21, 0x20001
	s_cmp_eq_u32 s3, 1
	s_cselect_b32 s1, 2, 0
	s_cmp_eq_u32 s3, 2
	s_cselect_b32 s1, -2, s1
	s_add_i32 s22, s22, s1
.Lp2_nodelta:
.LBB0_204:
	s_ashr_i32 s21, s20, 31
	s_lshl_b64 s[24:25], s[20:21], 20
	v_readlane_b32 s26, v236, 50
	v_readlane_b32 s27, v236, 51
	s_add_u32 s24, s26, s24
	s_addc_u32 s25, s27, s25
	s_and_b64 s[26:27], s[8:9], exec
	s_cselect_b32 s1, s25, s5
	s_cselect_b32 s3, s24, s4
	s_ashr_i32 s23, s22, 31
	s_lshl_b64 s[26:27], s[22:23], 20
	s_add_u32 s26, s10, s26
	s_addc_u32 s27, s11, s27
	s_and_b64 s[28:29], s[8:9], exec
	s_cselect_b32 s21, s27, s7
	s_cselect_b32 s23, s26, s6
	s_add_u32 s4, s4, 0x80080
	s_addc_u32 s5, s5, 0
	s_add_u32 s33, s6, 0x100
	v_mov_b32_e32 v0, 0
	s_addc_u32 s50, s7, 0
	s_mov_b32 s51, -2
	v_mov_b32_e32 v1, v0
	v_mov_b32_e32 v2, v0
	v_mov_b32_e32 v3, v0
	v_mov_b32_e32 v4, v0
	v_mov_b32_e32 v5, v0
	v_mov_b32_e32 v6, v0
	v_mov_b32_e32 v7, v0
	s_waitcnt vmcnt(0)
	v_mov_b32_e32 v16, v0
	v_mov_b32_e32 v17, v0
	v_mov_b32_e32 v18, v0
	v_mov_b32_e32 v19, v0
	v_mov_b32_e32 v20, v0
	v_mov_b32_e32 v21, v0
	v_mov_b32_e32 v22, v0
	v_mov_b32_e32 v23, v0
	v_mov_b32_e32 v32, v0
	v_mov_b32_e32 v33, v0
	v_mov_b32_e32 v34, v0
	v_mov_b32_e32 v35, v0
	v_mov_b32_e32 v36, v0
	v_mov_b32_e32 v37, v0
	v_mov_b32_e32 v38, v0
	v_mov_b32_e32 v39, v0
	v_mov_b32_e32 v48, v0
	v_mov_b32_e32 v49, v0
	v_mov_b32_e32 v50, v0
	v_mov_b32_e32 v51, v0
	v_mov_b32_e32 v52, v0
	v_mov_b32_e32 v53, v0
	v_mov_b32_e32 v54, v0
	v_mov_b32_e32 v55, v0
	v_mov_b32_e32 v8, v0
	v_mov_b32_e32 v9, v0
	v_mov_b32_e32 v10, v0
	v_mov_b32_e32 v11, v0
	v_mov_b32_e32 v12, v0
	v_mov_b32_e32 v13, v0
	v_mov_b32_e32 v14, v0
	v_mov_b32_e32 v15, v0
	v_mov_b32_e32 v24, v0
	v_mov_b32_e32 v25, v0
	v_mov_b32_e32 v26, v0
	v_mov_b32_e32 v27, v0
	v_mov_b32_e32 v28, v0
	v_mov_b32_e32 v29, v0
	v_mov_b32_e32 v30, v0
	v_mov_b32_e32 v31, v0
	v_mov_b32_e32 v40, v0
	v_mov_b32_e32 v41, v0
	v_mov_b32_e32 v42, v0
	v_mov_b32_e32 v43, v0
	v_mov_b32_e32 v44, v0
	v_mov_b32_e32 v45, v0
	v_mov_b32_e32 v46, v0
	v_mov_b32_e32 v47, v0
	v_mov_b32_e32 v56, v0
	v_mov_b32_e32 v57, v0
	v_mov_b32_e32 v58, v0
	v_mov_b32_e32 v59, v0
	v_mov_b32_e32 v60, v0
	v_mov_b32_e32 v61, v0
	v_mov_b32_e32 v62, v0
	v_mov_b32_e32 v63, v0
	v_mov_b32_e32 v64, v0
	v_mov_b32_e32 v65, v0
	v_mov_b32_e32 v66, v0
	v_mov_b32_e32 v67, v0
	v_mov_b32_e32 v68, v0
	v_mov_b32_e32 v69, v0
	v_mov_b32_e32 v70, v0
	v_mov_b32_e32 v71, v0
	v_mov_b32_e32 v80, v0
	v_mov_b32_e32 v81, v0
	v_mov_b32_e32 v82, v0
	v_mov_b32_e32 v83, v0
	v_mov_b32_e32 v84, v0
	v_mov_b32_e32 v85, v0
	v_mov_b32_e32 v86, v0
	v_mov_b32_e32 v87, v0
	v_mov_b32_e32 v96, v0
	v_mov_b32_e32 v97, v0
	v_mov_b32_e32 v98, v0
	v_mov_b32_e32 v99, v0
	v_mov_b32_e32 v100, v0
	v_mov_b32_e32 v101, v0
	v_mov_b32_e32 v102, v0
	v_mov_b32_e32 v103, v0
	v_mov_b32_e32 v112, v0
	v_mov_b32_e32 v113, v0
	v_mov_b32_e32 v114, v0
	v_mov_b32_e32 v115, v0
	v_mov_b32_e32 v116, v0
	v_mov_b32_e32 v117, v0
	v_mov_b32_e32 v118, v0
	v_mov_b32_e32 v119, v0
	v_mov_b32_e32 v72, v0
	v_mov_b32_e32 v73, v0
	v_mov_b32_e32 v74, v0
	v_mov_b32_e32 v75, v0
	v_mov_b32_e32 v76, v0
	v_mov_b32_e32 v77, v0
	v_mov_b32_e32 v78, v0
	v_mov_b32_e32 v79, v0
	v_mov_b32_e32 v88, v0
	v_mov_b32_e32 v89, v0
	v_mov_b32_e32 v90, v0
	v_mov_b32_e32 v91, v0
	v_mov_b32_e32 v92, v0
	v_mov_b32_e32 v93, v0
	v_mov_b32_e32 v94, v0
	v_mov_b32_e32 v95, v0
	v_mov_b32_e32 v104, v0
	v_mov_b32_e32 v105, v0
	v_mov_b32_e32 v106, v0
	v_mov_b32_e32 v107, v0
	v_mov_b32_e32 v108, v0
	v_mov_b32_e32 v109, v0
	v_mov_b32_e32 v110, v0
	v_mov_b32_e32 v111, v0
	v_mov_b32_e32 v120, v0
	v_mov_b32_e32 v121, v0
	v_mov_b32_e32 v122, v0
	v_mov_b32_e32 v123, v0
	v_mov_b32_e32 v124, v0
	v_mov_b32_e32 v125, v0
	v_mov_b32_e32 v126, v0
	v_mov_b32_e32 v127, v0
